# M3 s5out block: 5 more operand loads hoisted into free quads v224-v243 (15 loads in flight instead of 10), counted waits loosened to match, both layers
# speedup vs baseline: 1.0053x; 1.0001x over previous
; __device__ __forceinline__ unsigned cvt_pk_bf16(float lo, float hi) { unsigned r; asm("v_cvt_pk_bf16_f32 %0, %1, %2" : "=v"(r) : "v"(lo), "v"(hi)); return r; }
; __device__ __forceinline__ void s5out_item(PRef p, int layer, int item, unsigned char* shm) {
;     ...
; #pragma unroll 4
;         for (int kk = 0; kk < 32; ++kk) {
;             const bf16x8 bfr = *(const bf16x8*)(ul + fr * S5_UP + kk * 64 + fq * 16);
;             const int sq = 2 * kk + (fq >> 1);
; #pragma unroll
;             for (int mi = 0; mi < 4; ++mi) { const bf16x8 af = *(const bf16x8*)(KT + (tb + mi - sq + 63) * 256 + fr * 16 + (fq & 1) * 8);
;                 acc[mi] = __builtin_amdgcn_mfma_f32_16x16x32_bf16(af, bfr, acc[mi], 0, 0, 0); } }
;         const int cidx = nt < 4 ? 4 + 16 * nt + fr : (fr & 3);
; #pragma unroll
;         for (int dir = 0; dir < 2; ++dir) {
;             const bf16_t* G = (const bf16_t*)(p.ws + O_S5G) + (size_t)(dir * 32 + g) * 1024 * 128;
;             const float* ST = (const float*)(p.ws + O_S5ST) + (size_t)((g * 2 + dir) * 4 + b) * 68 * 128 + (size_t)cidx * 128;
; #pragma unroll
;             for (int kk = 0; kk < 4; ++kk) {
;                 const f32x4 x0 = *(const f32x4*)(ST + kk * 32 + fq * 8), x1 = *(const f32x4*)(ST + kk * 32 + fq * 8 + 4);
;                 u32x4 w; w.x = cvt_pk_bf16(x0[0], x0[1]); w.y = cvt_pk_bf16(x0[2], x0[3]); w.z = cvt_pk_bf16(x1[0], x1[1]); w.w = cvt_pk_bf16(x1[2], x1[3]);
;                 const bf16x8 bfr = mk8(w);
; #pragma unroll
;                 for (int mi = 0; mi < 4; ++mi) { const bf16x8 af = *(const bf16x8*)(G + (size_t)((tb + mi) * 16 + fr) * 128 + kk * 32 + fq * 8);
;                     acc[mi] = __builtin_amdgcn_mfma_f32_16x16x32_bf16(af, bfr, acc[mi], 0, 0, 0); } } }
.LBB0_417:
	v_add_u32_e32 v43, s50, v81
	ds_read_b128 v[44:47], v42
	ds_read_b128 v[90:93], v42 offset:64
	ds_read_b128 v[94:97], v43 offset:32256
	ds_read_b128 v[98:101], v43 offset:32768
	ds_read_b128 v[102:105], v43 offset:31744
	ds_read_b128 v[106:109], v43 offset:33280
	s_waitcnt lgkmcnt(3)
	v_mfma_f32_16x16x32_bf16 v[16:19], v[94:97], v[44:47], v[16:19]
	s_addk_i32 s50, 0xf000
	s_cmpk_eq_i32 s50, 0x8000
	s_waitcnt lgkmcnt(2)
	v_mfma_f32_16x16x32_bf16 v[12:15], v[98:101], v[44:47], v[12:15]
	s_waitcnt lgkmcnt(0)
	v_mfma_f32_16x16x32_bf16 v[8:11], v[106:109], v[44:47], v[8:11]
	ds_read_b128 v[106:109], v43 offset:33792
	ds_read_b128 v[110:113], v43 offset:29184
	s_waitcnt lgkmcnt(1)
	v_mfma_f32_16x16x32_bf16 v[4:7], v[106:109], v[44:47], v[4:7]
	ds_read_b128 v[44:47], v43 offset:31232
	ds_read_b128 v[106:109], v43 offset:30720
	s_waitcnt lgkmcnt(1)
	v_mfma_f32_16x16x32_bf16 v[16:19], v[44:47], v[90:93], v[16:19]
	v_mfma_f32_16x16x32_bf16 v[12:15], v[102:105], v[90:93], v[12:15]
	v_mfma_f32_16x16x32_bf16 v[8:11], v[94:97], v[90:93], v[8:11]
	ds_read_b128 v[94:97], v42 offset:128
	ds_read_b128 v[114:117], v42 offset:192
	v_add_u32_e32 v42, 0x100, v42
	v_mfma_f32_16x16x32_bf16 v[4:7], v[98:101], v[90:93], v[4:7]
	ds_read_b128 v[90:93], v43 offset:30208
	ds_read_b128 v[98:101], v43 offset:29696
	s_waitcnt lgkmcnt(1)
	v_mfma_f32_16x16x32_bf16 v[16:19], v[90:93], v[94:97], v[16:19]
	v_mfma_f32_16x16x32_bf16 v[12:15], v[106:109], v[94:97], v[12:15]
	v_mfma_f32_16x16x32_bf16 v[8:11], v[44:47], v[94:97], v[8:11]
	v_mfma_f32_16x16x32_bf16 v[4:7], v[102:105], v[94:97], v[4:7]
	v_mfma_f32_16x16x32_bf16 v[16:19], v[110:113], v[114:117], v[16:19]
	s_waitcnt lgkmcnt(0)
	v_mfma_f32_16x16x32_bf16 v[12:15], v[98:101], v[114:117], v[12:15]
	v_mfma_f32_16x16x32_bf16 v[8:11], v[90:93], v[114:117], v[8:11]
	v_mfma_f32_16x16x32_bf16 v[4:7], v[106:109], v[114:117], v[4:7]
	s_cbranch_scc0 .LBB0_417
	v_lshl_add_u32 v42, s22, 4, v73
	v_cndmask_b32_e64 v42, v74, v42, s[4:5]
	v_mov_b32_e32 v43, v33
	v_lshlrev_b64 v[42:43], 9, v[42:43]
	v_lshl_add_u64 v[130:131], v[20:21], 0, v[42:43]
	v_lshl_add_u64 v[132:133], v[130:131], 0, s[46:47]
	global_load_dwordx4 v[42:45], v[24:25], off
	global_load_dwordx4 v[46:49], v[132:133], off
	global_load_dwordx4 v[90:93], v[132:133], off offset:16
	global_load_dwordx4 v[94:97], v[26:27], off
	global_load_dwordx4 v[98:101], v[28:29], off
	global_load_dwordx4 v[102:105], v[30:31], off
	global_load_dwordx4 v[106:109], v[132:133], off offset:128
	global_load_dwordx4 v[110:113], v[24:25], off offset:64
	global_load_dwordx4 v[114:117], v[132:133], off offset:144
	global_load_dwordx4 v[118:121], v[26:27], off offset:64
	global_load_dwordx4 v[224:227], v[28:29], off offset:64
	global_load_dwordx4 v[228:231], v[30:31], off offset:64
	global_load_dwordx4 v[232:235], v[132:133], off offset:256
	global_load_dwordx4 v[236:239], v[24:25], off offset:128
	global_load_dwordx4 v[240:243], v[132:133], off offset:272
	s_or_b64 s[68:69], s[4:5], s[2:3]
	s_waitcnt vmcnt(13)
	v_cvt_pk_bf16_f32 v46, v46, v47
	v_cvt_pk_bf16_f32 v47, v48, v49
	s_waitcnt vmcnt(12)
	v_cvt_pk_bf16_f32 v48, v90, v91
	v_cvt_pk_bf16_f32 v49, v92, v93
	s_waitcnt vmcnt(8)
	v_cvt_pk_bf16_f32 v106, v106, v107
	v_mfma_f32_16x16x32_bf16 v[16:19], v[42:45], v[46:49], v[16:19]
	v_cvt_pk_bf16_f32 v107, v108, v109
	s_waitcnt vmcnt(6)
	v_cvt_pk_bf16_f32 v108, v114, v115
	v_mfma_f32_16x16x32_bf16 v[12:15], v[94:97], v[46:49], v[12:15]
	v_cvt_pk_bf16_f32 v109, v116, v117
	s_waitcnt vmcnt(2)
	v_cvt_pk_bf16_f32 v232, v232, v233
	v_mfma_f32_16x16x32_bf16 v[8:11], v[98:101], v[46:49], v[8:11]
	global_load_dwordx4 v[126:129], v[26:27], off offset:128
	v_cvt_pk_bf16_f32 v233, v234, v235
	s_waitcnt vmcnt(1)
	v_cvt_pk_bf16_f32 v234, v240, v241
	v_mfma_f32_16x16x32_bf16 v[4:7], v[102:105], v[46:49], v[4:7]
	global_load_dwordx4 v[46:49], v[28:29], off offset:128
	v_cvt_pk_bf16_f32 v235, v242, v243
	v_mfma_f32_16x16x32_bf16 v[16:19], v[110:113], v[106:109], v[16:19]
	global_load_dwordx4 v[102:105], v[30:31], off offset:128
	global_load_dwordx4 v[110:113], v[132:133], off offset:400
	global_load_dwordx4 v[114:117], v[132:133], off offset:384
	s_waitcnt vmcnt(0)
	v_cvt_pk_bf16_f32 v114, v114, v115
	v_mfma_f32_16x16x32_bf16 v[12:15], v[118:121], v[106:109], v[12:15]
	v_cvt_pk_bf16_f32 v115, v116, v117
	v_cvt_pk_bf16_f32 v116, v110, v111
	v_cvt_pk_bf16_f32 v117, v112, v113
	v_mfma_f32_16x16x32_bf16 v[8:11], v[224:227], v[106:109], v[8:11]
	global_load_dwordx4 v[42:45], v[24:25], off offset:192
	global_load_dwordx4 v[118:121], v[26:27], off offset:192
	v_mfma_f32_16x16x32_bf16 v[4:7], v[228:231], v[106:109], v[4:7]
	global_load_dwordx4 v[90:93], v[28:29], off offset:192
	global_load_dwordx4 v[98:101], v[30:31], off offset:192
	v_mfma_f32_16x16x32_bf16 v[12:15], v[126:129], v[232:235], v[12:15]
	v_lshl_add_u64 v[126:127], v[130:131], 0, s[48:49]
	v_mfma_f32_16x16x32_bf16 v[16:19], v[236:239], v[232:235], v[16:19]
	global_load_dwordx4 v[106:109], v[126:127], off
	global_load_dwordx4 v[122:125], v[34:35], off
	s_waitcnt vmcnt(1)
	v_cvt_pk_bf16_f32 v106, v106, v107
	v_mfma_f32_16x16x32_bf16 v[8:11], v[46:49], v[232:235], v[8:11]
	global_load_dwordx4 v[46:49], v[126:127], off offset:16
	v_cvt_pk_bf16_f32 v107, v108, v109
	v_mfma_f32_16x16x32_bf16 v[16:19], v[42:45], v[114:117], v[16:19]
	global_load_dwordx4 v[42:45], v[36:37], off
	s_waitcnt vmcnt(1)
; __device__ __forceinline__ unsigned cvt_pk_bf16(float lo, float hi) { unsigned r; asm("v_cvt_pk_bf16_f32 %0, %1, %2" : "=v"(r) : "v"(lo), "v"(hi)); return r; }
; __device__ __forceinline__ void s5out_item(PRef p, int layer, int item, unsigned char* shm) {
;     ...
;         for (int dir = 0; dir < 2; ++dir) {
;             const bf16_t* G = (const bf16_t*)(p.ws + O_S5G) + (size_t)(dir * 32 + g) * 1024 * 128;
;             const float* ST = (const float*)(p.ws + O_S5ST) + (size_t)((g * 2 + dir) * 4 + b) * 68 * 128 + (size_t)cidx * 128;
; #pragma unroll
;             for (int kk = 0; kk < 4; ++kk) {
;                 const f32x4 x0 = *(const f32x4*)(ST + kk * 32 + fq * 8), x1 = *(const f32x4*)(ST + kk * 32 + fq * 8 + 4);
;                 u32x4 w; w.x = cvt_pk_bf16(x0[0], x0[1]); w.y = cvt_pk_bf16(x0[2], x0[3]); w.z = cvt_pk_bf16(x1[0], x1[1]); w.w = cvt_pk_bf16(x1[2], x1[3]);
;                 const bf16x8 bfr = mk8(w);
; #pragma unroll
;                 for (int mi = 0; mi < 4; ++mi) { const bf16x8 af = *(const bf16x8*)(G + (size_t)((tb + mi) * 16 + fr) * 128 + kk * 32 + fq * 8);
;                     acc[mi] = __builtin_amdgcn_mfma_f32_16x16x32_bf16(af, bfr, acc[mi], 0, 0, 0); } } }
	v_cvt_pk_bf16_f32 v108, v46, v47
	v_cvt_pk_bf16_f32 v109, v48, v49
	v_mfma_f32_16x16x32_bf16 v[4:7], v[102:105], v[232:235], v[4:7]
	global_load_dwordx4 v[94:97], v[38:39], off
	global_load_dwordx4 v[102:105], v[40:41], off
	global_load_dwordx4 v[110:113], v[34:35], off offset:64
	v_mfma_f32_16x16x32_bf16 v[12:15], v[118:121], v[114:117], v[12:15]
	v_mfma_f32_16x16x32_bf16 v[8:11], v[90:93], v[114:117], v[8:11]
	global_load_dwordx4 v[90:93], v[126:127], off offset:144
	global_load_dwordx4 v[118:121], v[126:127], off offset:128
	global_load_dwordx4 v[46:49], v[36:37], off offset:64
	s_waitcnt vmcnt(1)
	v_cvt_pk_bf16_f32 v118, v118, v119
	v_mfma_f32_16x16x32_bf16 v[4:7], v[98:101], v[114:117], v[4:7]
	v_cvt_pk_bf16_f32 v119, v120, v121
	v_cvt_pk_bf16_f32 v120, v90, v91
	v_cvt_pk_bf16_f32 v121, v92, v93
	v_mfma_f32_16x16x32_bf16 v[16:19], v[122:125], v[106:109], v[16:19]
	v_mfma_f32_16x16x32_bf16 v[12:15], v[42:45], v[106:109], v[12:15]
	global_load_dwordx4 v[42:45], v[38:39], off offset:64
	global_load_dwordx4 v[98:101], v[40:41], off offset:64
	global_load_dwordx4 v[114:117], v[34:35], off offset:128
	v_mfma_f32_16x16x32_bf16 v[8:11], v[94:97], v[106:109], v[8:11]
	global_load_dwordx4 v[94:97], v[126:127], off offset:272
	global_load_dwordx4 v[122:125], v[126:127], off offset:256
	global_load_dwordx4 v[90:93], v[36:37], off offset:128
	s_waitcnt vmcnt(1)
	v_cvt_pk_bf16_f32 v122, v122, v123
	v_mfma_f32_16x16x32_bf16 v[4:7], v[102:105], v[106:109], v[4:7]
	v_cvt_pk_bf16_f32 v123, v124, v125
	v_cvt_pk_bf16_f32 v124, v94, v95
	v_cvt_pk_bf16_f32 v125, v96, v97
	v_mfma_f32_16x16x32_bf16 v[12:15], v[46:49], v[118:121], v[12:15]
	global_load_dwordx4 v[46:49], v[38:39], off offset:128
	global_load_dwordx4 v[102:105], v[40:41], off offset:128
	global_load_dwordx4 v[106:109], v[34:35], off offset:192
	v_mfma_f32_16x16x32_bf16 v[8:11], v[42:45], v[118:121], v[8:11]
	v_mfma_f32_16x16x32_bf16 v[16:19], v[110:113], v[118:121], v[16:19]
	global_load_dwordx4 v[42:45], v[126:127], off offset:400
	global_load_dwordx4 v[110:113], v[126:127], off offset:384
	global_load_dwordx4 v[94:97], v[36:37], off offset:192
	s_waitcnt vmcnt(6)
	v_mfma_f32_16x16x32_bf16 v[12:15], v[90:93], v[122:125], v[12:15]
	global_load_dwordx4 v[90:93], v[38:39], off offset:192
	s_waitcnt vmcnt(6)
	v_mfma_f32_16x16x32_bf16 v[8:11], v[46:49], v[122:125], v[8:11]
	global_load_dwordx4 v[46:49], v[40:41], off offset:192
	v_mfma_f32_16x16x32_bf16 v[4:7], v[98:101], v[118:121], v[4:7]
	s_waitcnt vmcnt(3)
	v_cvt_pk_bf16_f32 v98, v110, v111
	v_mfma_f32_16x16x32_bf16 v[16:19], v[114:117], v[122:125], v[16:19]
	v_cvt_pk_bf16_f32 v99, v112, v113
	v_cvt_pk_bf16_f32 v100, v42, v43
	v_cvt_pk_bf16_f32 v101, v44, v45
	v_mfma_f32_16x16x32_bf16 v[4:7], v[102:105], v[122:125], v[4:7]
	v_mfma_f32_16x16x32_bf16 v[16:19], v[106:109], v[98:101], v[16:19]
	s_waitcnt vmcnt(2)
	v_mfma_f32_16x16x32_bf16 v[12:15], v[94:97], v[98:101], v[12:15]
	s_waitcnt vmcnt(1)
	v_mfma_f32_16x16x32_bf16 v[8:11], v[90:93], v[98:101], v[8:11]
	s_waitcnt vmcnt(0)
	v_mfma_f32_16x16x32_bf16 v[4:7], v[46:49], v[98:101], v[4:7]
	s_and_saveexec_b64 s[50:51], s[68:69]
	s_cbranch_execz .LBB0_415
; __device__ __forceinline__ unsigned cvt_pk_bf16(float lo, float hi) { unsigned r; asm("v_cvt_pk_bf16_f32 %0, %1, %2" : "=v"(r) : "v"(lo), "v"(hi)); return r; }
; __device__ __forceinline__ float bflo(unsigned w) { return __uint_as_float(w << 16); }
; __device__ __forceinline__ float bfhi(unsigned w) { return __uint_as_float(w & 0xffff0000u); }
; __device__ __forceinline__ float gelu_tanh(float x) { const float u = 0.7978845608028654f * (x + 0.044715f * x * x * x); return x / (1.f + __expf(-2.f * u)); }
; __device__ __forceinline__ void s5out_item(PRef p, int layer, int item, unsigned char* shm) {
;     ...
;         if (nt < 4 || fr < 4) {
; #pragma unroll
;             for (int mi = 0; mi < 4; ++mi) { const int t = tb + mi; const size_t row = nt < 4 ? (size_t)(b * 4096 + (16 * nt + fr) * 64 + t) : (size_t)(RL + b * 256 + fr * 64 + t);
;                 const u32x2 uu = *(const u32x2*)(ul + fr * S5_UP + t * 32 + fq * 8);
;                 const f32x4 y = acc[mi];
;                 u32x2 w; w.x = cvt_pk_bf16(gelu_tanh(y[0] + dv[0] * bflo(uu.x)), gelu_tanh(y[1] + dv[1] * bfhi(uu.x)));
;                 w.y = cvt_pk_bf16(gelu_tanh(y[2] + dv[2] * bflo(uu.y)), gelu_tanh(y[3] + dv[3] * bfhi(uu.y)));
;                 *(u32x2*)(Z + row * 512 + g * 16 + fq * 4) = w; } }
	ds_read_b64 v[42:43], v86 offset:65024
	ds_read_b64 v[44:45], v87 offset:65024
	ds_read_b64 v[48:49], v88 offset:65024
	ds_read_b64 v[46:47], v89 offset:65024
	s_waitcnt lgkmcnt(3)
	v_lshlrev_b32_e32 v90, 16, v42
	v_fma_f32 v16, v0, v90, v16
	v_mul_f32_e32 v90, 0x3d372713, v16
	v_mul_f32_e32 v90, v16, v90
	v_fma_f32 v90, v16, v90, v16
	v_mul_f32_e32 v90, 0xc0135761, v90
	v_exp_f32_e32 v91, v90
	v_add_u32_e32 v90, s12, v76
	v_cndmask_b32_e64 v92, v75, v90, s[4:5]
	v_and_b32_e32 v42, 0xffff0000, v42
	v_add_f32_e32 v93, 1.0, v91
	v_rcp_f32_e32 v95, v93
	v_fma_f32 v17, v1, v42, v17
	v_mul_f32_e32 v42, 0x3d372713, v17
	v_mul_f32_e32 v42, v17, v42
	v_fma_f32 v42, v17, v42, v17
	v_mul_f32_e32 v42, 0xc0135761, v42
	v_exp_f32_e32 v42, v42
	v_mul_f32_e32 v94, v16, v95
	v_lshlrev_b32_e32 v95, 16, v43
	v_fma_f32 v18, v2, v95, v18
	v_add_f32_e32 v42, 1.0, v42
	v_mul_f32_e32 v95, 0x3d372713, v18
	v_mul_f32_e32 v95, v18, v95
	v_rcp_f32_e32 v98, v42
	v_fma_f32 v95, v18, v95, v18
	v_mul_f32_e32 v95, 0xc0135761, v95
	v_mov_b32_e32 v16, v94
	v_exp_f32_e32 v95, v95
	v_and_b32_e32 v43, 0xffff0000, v43
	v_fmac_f32_e32 v19, v3, v43
	v_mul_f32_e32 v43, 0x3d372713, v19
	v_add_f32_e32 v95, 1.0, v95
	v_mul_f32_e32 v43, v19, v43
	v_fma_f32 v43, v19, v43, v19
	v_rcp_f32_e32 v97, v95
	v_mul_f32_e32 v43, 0xc0135761, v43
	v_mul_f32_e32 v17, v17, v98
	v_exp_f32_e32 v43, v43
	v_cvt_pk_bf16_f32 v16, v16, v17
	v_add_f32_e32 v43, 1.0, v43
	v_rcp_f32_e32 v94, v43
	v_mul_f32_e32 v17, v18, v97
	v_mul_f32_e32 v18, v19, v94
	s_waitcnt lgkmcnt(2)
	v_lshlrev_b32_e32 v19, 16, v44
	v_fma_f32 v12, v0, v19, v12
	v_mul_f32_e32 v19, 0x3d372713, v12
	v_mul_f32_e32 v19, v12, v19
	v_fma_f32 v19, v12, v19, v12
	v_mul_f32_e32 v19, 0xc0135761, v19
	v_exp_f32_e32 v42, v19
	v_and_b32_e32 v44, 0xffff0000, v44
	v_add_u32_e32 v90, v92, v63
	v_fma_f32 v13, v1, v44, v13
	v_add_f32_e32 v42, 1.0, v42
	v_ashrrev_i32_e32 v91, 31, v90
	v_mul_f32_e32 v44, 0x3d372713, v13
	v_cvt_pk_bf16_f32 v17, v17, v18
	v_lshlrev_b64 v[18:19], 10, v[90:91]
	v_rcp_f32_e32 v90, v42
	v_mul_f32_e32 v44, v13, v44
	v_fma_f32 v44, v13, v44, v13
	v_mul_f32_e32 v44, 0xc0135761, v44
	v_lshl_add_u64 v[18:19], v[22:23], 0, v[18:19]
	global_store_dwordx2 v[18:19], v[16:17], off
	v_exp_f32_e32 v44, v44
	s_nop 0
	v_add_f32_e32 v43, 1.0, v44
	v_rcp_f32_e32 v91, v43
	v_mul_f32_e32 v12, v12, v90
	v_lshlrev_b32_e32 v42, 16, v45
	v_fma_f32 v14, v2, v42, v14
	v_mul_f32_e32 v42, 0x3d372713, v14
	v_mul_f32_e32 v42, v14, v42
	v_fma_f32 v42, v14, v42, v14
	v_mul_f32_e32 v42, 0xc0135761, v42
	v_exp_f32_e32 v42, v42
	v_and_b32_e32 v19, 0xffff0000, v45
	v_fmac_f32_e32 v15, v3, v19
	v_mul_f32_e32 v19, 0x3d372713, v15
	v_add_f32_e32 v42, 1.0, v42
	v_mul_f32_e32 v19, v15, v19
	v_fma_f32 v19, v15, v19, v15
	v_rcp_f32_e32 v90, v42
	v_mul_f32_e32 v19, 0xc0135761, v19
	v_mul_f32_e32 v13, v13, v91
	v_exp_f32_e32 v19, v19
	v_cvt_pk_bf16_f32 v12, v12, v13
	v_add_f32_e32 v19, 1.0, v19
	v_rcp_f32_e32 v44, v19
	v_mul_f32_e32 v13, v14, v90
	v_add_u32_e32 v16, v92, v77
	v_mul_f32_e32 v14, v15, v44
	s_waitcnt lgkmcnt(1)
	v_lshlrev_b32_e32 v15, 16, v48
	v_fma_f32 v8, v0, v15, v8
	v_mul_f32_e32 v15, 0x3d372713, v8
	v_mul_f32_e32 v15, v8, v15
	v_fma_f32 v15, v8, v15, v8
	v_mul_f32_e32 v15, 0xc0135761, v15
	v_exp_f32_e32 v18, v15
	v_ashrrev_i32_e32 v17, 31, v16
	v_and_b32_e32 v19, 0xffff0000, v48
	v_cvt_pk_bf16_f32 v13, v13, v14
	v_lshlrev_b64 v[14:15], 10, v[16:17]
	v_add_f32_e32 v16, 1.0, v18
	v_fma_f32 v9, v1, v19, v9
	v_mul_f32_e32 v19, 0x3d372713, v9
	v_rcp_f32_e32 v18, v16
	v_mul_f32_e32 v19, v9, v19
	v_fma_f32 v19, v9, v19, v9
	v_mul_f32_e32 v19, 0xc0135761, v19
	v_lshl_add_u64 v[14:15], v[22:23], 0, v[14:15]
	global_store_dwordx2 v[14:15], v[12:13], off
	v_exp_f32_e32 v19, v19
	s_nop 0
	v_add_f32_e32 v17, 1.0, v19
	v_rcp_f32_e32 v42, v17
	v_mul_f32_e32 v8, v8, v18
	v_lshlrev_b32_e32 v16, 16, v49
	v_fma_f32 v10, v2, v16, v10
	v_mul_f32_e32 v16, 0x3d372713, v10
	v_mul_f32_e32 v16, v10, v16
	v_fma_f32 v16, v10, v16, v10
	v_mul_f32_e32 v16, 0xc0135761, v16
	v_exp_f32_e32 v16, v16
	v_and_b32_e32 v15, 0xffff0000, v49
	v_fmac_f32_e32 v11, v3, v15
	v_mul_f32_e32 v15, 0x3d372713, v11
	v_add_f32_e32 v16, 1.0, v16
	v_mul_f32_e32 v15, v11, v15
	v_fma_f32 v15, v11, v15, v11
	v_rcp_f32_e32 v19, v16
	v_mul_f32_e32 v15, 0xc0135761, v15
	v_mul_f32_e32 v9, v9, v42
	v_exp_f32_e32 v15, v15
	v_cvt_pk_bf16_f32 v8, v8, v9
	v_add_f32_e32 v15, 1.0, v15
	v_rcp_f32_e32 v18, v15
	v_mul_f32_e32 v9, v10, v19
	v_add_u32_e32 v12, v92, v78
	v_mul_f32_e32 v10, v11, v18
	s_waitcnt lgkmcnt(0)
	v_lshlrev_b32_e32 v11, 16, v46
	v_fma_f32 v4, v0, v11, v4
	v_mul_f32_e32 v11, 0x3d372713, v4
	v_mul_f32_e32 v11, v4, v11
	v_fma_f32 v11, v4, v11, v4
	v_mul_f32_e32 v11, 0xc0135761, v11
	v_exp_f32_e32 v14, v11
	v_ashrrev_i32_e32 v13, 31, v12
	v_and_b32_e32 v15, 0xffff0000, v46
	v_cvt_pk_bf16_f32 v9, v9, v10
	v_lshlrev_b64 v[10:11], 10, v[12:13]
	v_add_f32_e32 v12, 1.0, v14
	v_fma_f32 v5, v1, v15, v5
	v_mul_f32_e32 v15, 0x3d372713, v5
	v_rcp_f32_e32 v14, v12
	v_mul_f32_e32 v15, v5, v15
	v_fma_f32 v15, v5, v15, v5
	v_mul_f32_e32 v15, 0xc0135761, v15
	v_lshl_add_u64 v[10:11], v[22:23], 0, v[10:11]
	global_store_dwordx2 v[10:11], v[8:9], off
	v_exp_f32_e32 v15, v15
	s_nop 0
	v_add_f32_e32 v13, 1.0, v15
	v_rcp_f32_e32 v16, v13
	v_mul_f32_e32 v4, v4, v14
	v_lshlrev_b32_e32 v12, 16, v47
	v_fma_f32 v6, v2, v12, v6
	v_mul_f32_e32 v12, 0x3d372713, v6
	v_mul_f32_e32 v12, v6, v12
	v_fma_f32 v12, v6, v12, v6
	v_mul_f32_e32 v12, 0xc0135761, v12
	v_exp_f32_e32 v12, v12
	v_and_b32_e32 v11, 0xffff0000, v47
	v_fmac_f32_e32 v7, v3, v11
	v_mul_f32_e32 v11, 0x3d372713, v7
	v_add_f32_e32 v12, 1.0, v12
	v_mul_f32_e32 v11, v7, v11
	v_fma_f32 v11, v7, v11, v7
	v_rcp_f32_e32 v15, v12
	v_mul_f32_e32 v11, 0xc0135761, v11
	v_mul_f32_e32 v5, v5, v16
	v_exp_f32_e32 v11, v11
	v_cvt_pk_bf16_f32 v4, v4, v5
	v_add_f32_e32 v11, 1.0, v11
	v_rcp_f32_e32 v14, v11
	v_mul_f32_e32 v5, v6, v15
	v_add_u32_e32 v8, v92, v79
	v_ashrrev_i32_e32 v9, 31, v8
	v_mul_f32_e32 v6, v7, v14
	v_cvt_pk_bf16_f32 v5, v5, v6
	v_lshlrev_b64 v[6:7], 10, v[8:9]
	v_lshl_add_u64 v[6:7], v[22:23], 0, v[6:7]
	global_store_dwordx2 v[6:7], v[4:5], off
	s_branch .LBB0_415

; __device__ __forceinline__ unsigned cvt_pk_bf16(float lo, float hi) { unsigned r; asm("v_cvt_pk_bf16_f32 %0, %1, %2" : "=v"(r) : "v"(lo), "v"(hi)); return r; }
; __device__ __forceinline__ void s5out_item(PRef p, int layer, int item, unsigned char* shm) {
;     ...
; #pragma unroll 4
;         for (int kk = 0; kk < 32; ++kk) {
;             const bf16x8 bfr = *(const bf16x8*)(ul + fr * S5_UP + kk * 64 + fq * 16);
;             const int sq = 2 * kk + (fq >> 1);
; #pragma unroll
;             for (int mi = 0; mi < 4; ++mi) { const bf16x8 af = *(const bf16x8*)(KT + (tb + mi - sq + 63) * 256 + fr * 16 + (fq & 1) * 8);
;                 acc[mi] = __builtin_amdgcn_mfma_f32_16x16x32_bf16(af, bfr, acc[mi], 0, 0, 0); } }
;         const int cidx = nt < 4 ? 4 + 16 * nt + fr : (fr & 3);
; #pragma unroll
;         for (int dir = 0; dir < 2; ++dir) {
;             const bf16_t* G = (const bf16_t*)(p.ws + O_S5G) + (size_t)(dir * 32 + g) * 1024 * 128;
;             const float* ST = (const float*)(p.ws + O_S5ST) + (size_t)((g * 2 + dir) * 4 + b) * 68 * 128 + (size_t)cidx * 128;
; #pragma unroll
;             for (int kk = 0; kk < 4; ++kk) {
;                 const f32x4 x0 = *(const f32x4*)(ST + kk * 32 + fq * 8), x1 = *(const f32x4*)(ST + kk * 32 + fq * 8 + 4);
;                 u32x4 w; w.x = cvt_pk_bf16(x0[0], x0[1]); w.y = cvt_pk_bf16(x0[2], x0[3]); w.z = cvt_pk_bf16(x1[0], x1[1]); w.w = cvt_pk_bf16(x1[2], x1[3]);
;                 const bf16x8 bfr = mk8(w);
; #pragma unroll
;                 for (int mi = 0; mi < 4; ++mi) { const bf16x8 af = *(const bf16x8*)(G + (size_t)((tb + mi) * 16 + fr) * 128 + kk * 32 + fq * 8);
;                     acc[mi] = __builtin_amdgcn_mfma_f32_16x16x32_bf16(af, bfr, acc[mi], 0, 0, 0); } } }
.LBB0_929:
	v_add_u32_e32 v21, s62, v87
	ds_read_b128 v[22:25], v20
	ds_read_b128 v[26:29], v20 offset:64
	ds_read_b128 v[54:57], v21 offset:32256
	ds_read_b128 v[58:61], v21 offset:32768
	ds_read_b128 v[96:99], v21 offset:31744
	ds_read_b128 v[100:103], v21 offset:33280
	s_waitcnt lgkmcnt(3)
	v_mfma_f32_16x16x32_bf16 v[16:19], v[54:57], v[22:25], v[16:19]
	s_addk_i32 s62, 0xf000
	s_cmpk_lg_i32 s62, 0x8000
	s_waitcnt lgkmcnt(2)
	v_mfma_f32_16x16x32_bf16 v[12:15], v[58:61], v[22:25], v[12:15]
	s_waitcnt lgkmcnt(0)
	v_mfma_f32_16x16x32_bf16 v[8:11], v[100:103], v[22:25], v[8:11]
	ds_read_b128 v[100:103], v21 offset:33792
	ds_read_b128 v[104:107], v21 offset:29184
	s_waitcnt lgkmcnt(1)
	v_mfma_f32_16x16x32_bf16 v[4:7], v[100:103], v[22:25], v[4:7]
	ds_read_b128 v[22:25], v21 offset:31232
	ds_read_b128 v[100:103], v21 offset:30720
	s_waitcnt lgkmcnt(1)
	v_mfma_f32_16x16x32_bf16 v[16:19], v[22:25], v[26:29], v[16:19]
	v_mfma_f32_16x16x32_bf16 v[12:15], v[96:99], v[26:29], v[12:15]
	v_mfma_f32_16x16x32_bf16 v[8:11], v[54:57], v[26:29], v[8:11]
	ds_read_b128 v[54:57], v20 offset:128
	ds_read_b128 v[108:111], v20 offset:192
	v_add_u32_e32 v20, 0x100, v20
	v_mfma_f32_16x16x32_bf16 v[4:7], v[58:61], v[26:29], v[4:7]
	ds_read_b128 v[26:29], v21 offset:30208
	ds_read_b128 v[58:61], v21 offset:29696
	s_waitcnt lgkmcnt(1)
	v_mfma_f32_16x16x32_bf16 v[16:19], v[26:29], v[54:57], v[16:19]
	v_mfma_f32_16x16x32_bf16 v[12:15], v[100:103], v[54:57], v[12:15]
	v_mfma_f32_16x16x32_bf16 v[8:11], v[22:25], v[54:57], v[8:11]
	v_mfma_f32_16x16x32_bf16 v[4:7], v[96:99], v[54:57], v[4:7]
	v_mfma_f32_16x16x32_bf16 v[16:19], v[104:107], v[108:111], v[16:19]
	s_waitcnt lgkmcnt(0)
	v_mfma_f32_16x16x32_bf16 v[12:15], v[58:61], v[108:111], v[12:15]
	v_mfma_f32_16x16x32_bf16 v[8:11], v[26:29], v[108:111], v[8:11]
	v_mfma_f32_16x16x32_bf16 v[4:7], v[100:103], v[108:111], v[4:7]
	s_cbranch_scc1 .LBB0_929
	v_lshl_add_u32 v20, s20, 4, v81
	v_mov_b32_e32 v21, v33
	v_lshlrev_b64 v[20:21], 9, v[20:21]
	v_lshl_add_u64 v[124:125], v[34:35], 0, v[20:21]
	v_lshl_add_u64 v[126:127], v[124:125], 0, s[36:37]
	global_load_dwordx4 v[20:23], v[38:39], off
	global_load_dwordx4 v[24:27], v[126:127], off
	global_load_dwordx4 v[28:31], v[126:127], off offset:16
	global_load_dwordx4 v[54:57], v[40:41], off
	global_load_dwordx4 v[58:61], v[42:43], off
	global_load_dwordx4 v[96:99], v[44:45], off
	global_load_dwordx4 v[100:103], v[126:127], off offset:128
	global_load_dwordx4 v[104:107], v[38:39], off offset:64
	global_load_dwordx4 v[108:111], v[126:127], off offset:144
	global_load_dwordx4 v[112:115], v[40:41], off offset:64
	global_load_dwordx4 v[224:227], v[42:43], off offset:64
	global_load_dwordx4 v[228:231], v[44:45], off offset:64
	global_load_dwordx4 v[232:235], v[126:127], off offset:256
	global_load_dwordx4 v[236:239], v[38:39], off offset:128
	global_load_dwordx4 v[240:243], v[126:127], off offset:272
	v_lshl_add_u64 v[124:125], v[124:125], 0, s[38:39]
	s_add_i32 s20, s20, 1
	s_cmp_lg_u32 s20, 4
	s_waitcnt vmcnt(13)
	v_cvt_pk_bf16_f32 v24, v24, v25
	v_cvt_pk_bf16_f32 v25, v26, v27
	s_waitcnt vmcnt(12)
	v_cvt_pk_bf16_f32 v26, v28, v29
	v_cvt_pk_bf16_f32 v27, v30, v31
	s_waitcnt vmcnt(8)
	v_cvt_pk_bf16_f32 v100, v100, v101
	v_mfma_f32_16x16x32_bf16 v[16:19], v[20:23], v[24:27], v[16:19]
	v_cvt_pk_bf16_f32 v101, v102, v103
	s_waitcnt vmcnt(6)
	v_cvt_pk_bf16_f32 v102, v108, v109
	v_mfma_f32_16x16x32_bf16 v[12:15], v[54:57], v[24:27], v[12:15]
	v_cvt_pk_bf16_f32 v103, v110, v111
	s_waitcnt vmcnt(2)
	v_cvt_pk_bf16_f32 v232, v232, v233
	v_mfma_f32_16x16x32_bf16 v[8:11], v[58:61], v[24:27], v[8:11]
	global_load_dwordx4 v[120:123], v[40:41], off offset:128
	v_cvt_pk_bf16_f32 v233, v234, v235
	s_waitcnt vmcnt(1)
	v_cvt_pk_bf16_f32 v234, v240, v241
	v_mfma_f32_16x16x32_bf16 v[4:7], v[96:99], v[24:27], v[4:7]
	global_load_dwordx4 v[24:27], v[42:43], off offset:128
	v_cvt_pk_bf16_f32 v235, v242, v243
	v_mfma_f32_16x16x32_bf16 v[16:19], v[104:107], v[100:103], v[16:19]
	global_load_dwordx4 v[96:99], v[44:45], off offset:128
	global_load_dwordx4 v[104:107], v[126:127], off offset:384
	global_load_dwordx4 v[108:111], v[38:39], off offset:192
	s_waitcnt vmcnt(1)
	v_cvt_pk_bf16_f32 v104, v104, v105
	v_mfma_f32_16x16x32_bf16 v[12:15], v[112:115], v[100:103], v[12:15]
	v_cvt_pk_bf16_f32 v105, v106, v107
	v_mfma_f32_16x16x32_bf16 v[8:11], v[224:227], v[100:103], v[8:11]
	global_load_dwordx4 v[20:23], v[126:127], off offset:400
	global_load_dwordx4 v[112:115], v[40:41], off offset:192
	s_waitcnt vmcnt(1)
	v_cvt_pk_bf16_f32 v106, v20, v21
	v_mfma_f32_16x16x32_bf16 v[4:7], v[228:231], v[100:103], v[4:7]
	global_load_dwordx4 v[28:31], v[42:43], off offset:192
	global_load_dwordx4 v[58:61], v[44:45], off offset:192
	v_cvt_pk_bf16_f32 v107, v22, v23
	v_mfma_f32_16x16x32_bf16 v[16:19], v[236:239], v[232:235], v[16:19]
	global_load_dwordx4 v[100:103], v[124:125], off
	global_load_dwordx4 v[116:119], v[46:47], off
	s_waitcnt vmcnt(1)
	v_cvt_pk_bf16_f32 v100, v100, v101
	v_mfma_f32_16x16x32_bf16 v[12:15], v[120:123], v[232:235], v[12:15]
	v_cvt_pk_bf16_f32 v101, v102, v103
	v_mfma_f32_16x16x32_bf16 v[8:11], v[24:27], v[232:235], v[8:11]
	global_load_dwordx4 v[24:27], v[124:125], off offset:16
	global_load_dwordx4 v[120:123], v[48:49], off
	global_load_dwordx4 v[20:23], v[50:51], off
	s_waitcnt vmcnt(2)
	v_cvt_pk_bf16_f32 v102, v24, v25
	v_mfma_f32_16x16x32_bf16 v[4:7], v[96:99], v[232:235], v[4:7]
	v_cvt_pk_bf16_f32 v103, v26, v27
	v_mfma_f32_16x16x32_bf16 v[16:19], v[108:111], v[104:107], v[16:19]
	global_load_dwordx4 v[54:57], v[52:53], off
	global_load_dwordx4 v[96:99], v[124:125], off offset:128
	global_load_dwordx4 v[108:111], v[46:47], off offset:64
	global_load_dwordx4 v[24:27], v[48:49], off offset:64
	s_waitcnt vmcnt(2)
; __device__ __forceinline__ unsigned cvt_pk_bf16(float lo, float hi) { unsigned r; asm("v_cvt_pk_bf16_f32 %0, %1, %2" : "=v"(r) : "v"(lo), "v"(hi)); return r; }
; __device__ __forceinline__ float bflo(unsigned w) { return __uint_as_float(w << 16); }
; __device__ __forceinline__ float bfhi(unsigned w) { return __uint_as_float(w & 0xffff0000u); }
; __device__ __forceinline__ float gelu_tanh(float x) { const float u = 0.7978845608028654f * (x + 0.044715f * x * x * x); return x / (1.f + __expf(-2.f * u)); }
; __device__ __forceinline__ void s5out_item(PRef p, int layer, int item, unsigned char* shm) {
;     ...
;         for (int dir = 0; dir < 2; ++dir) {
;             const bf16_t* G = (const bf16_t*)(p.ws + O_S5G) + (size_t)(dir * 32 + g) * 1024 * 128;
;             const float* ST = (const float*)(p.ws + O_S5ST) + (size_t)((g * 2 + dir) * 4 + b) * 68 * 128 + (size_t)cidx * 128;
; #pragma unroll
;             for (int kk = 0; kk < 4; ++kk) {
;                 const f32x4 x0 = *(const f32x4*)(ST + kk * 32 + fq * 8), x1 = *(const f32x4*)(ST + kk * 32 + fq * 8 + 4);
;                 u32x4 w; w.x = cvt_pk_bf16(x0[0], x0[1]); w.y = cvt_pk_bf16(x0[2], x0[3]); w.z = cvt_pk_bf16(x1[0], x1[1]); w.w = cvt_pk_bf16(x1[2], x1[3]);
;                 const bf16x8 bfr = mk8(w);
; #pragma unroll
;                 for (int mi = 0; mi < 4; ++mi) { const bf16x8 af = *(const bf16x8*)(G + (size_t)((tb + mi) * 16 + fr) * 128 + kk * 32 + fq * 8);
;                     acc[mi] = __builtin_amdgcn_mfma_f32_16x16x32_bf16(af, bfr, acc[mi], 0, 0, 0); } } }
;         if (nt < 4 || fr < 4) {
; #pragma unroll
;             for (int mi = 0; mi < 4; ++mi) { const int t = tb + mi; const size_t row = nt < 4 ? (size_t)(b * 4096 + (16 * nt + fr) * 64 + t) : (size_t)(RL + b * 256 + fr * 64 + t);
;                 const u32x2 uu = *(const u32x2*)(ul + fr * S5_UP + t * 32 + fq * 8);
;                 const f32x4 y = acc[mi];
;                 u32x2 w; w.x = cvt_pk_bf16(gelu_tanh(y[0] + dv[0] * bflo(uu.x)), gelu_tanh(y[1] + dv[1] * bfhi(uu.x)));
;                 w.y = cvt_pk_bf16(gelu_tanh(y[2] + dv[2] * bflo(uu.y)), gelu_tanh(y[3] + dv[3] * bfhi(uu.y)));
;                 *(u32x2*)(Z + row * 512 + g * 16 + fq * 4) = w; } }
	v_cvt_pk_bf16_f32 v96, v96, v97
	v_mfma_f32_16x16x32_bf16 v[8:11], v[28:31], v[104:107], v[8:11]
	global_load_dwordx4 v[28:31], v[124:125], off offset:144
	v_cvt_pk_bf16_f32 v97, v98, v99
	s_waitcnt vmcnt(0)
	v_cvt_pk_bf16_f32 v98, v28, v29
	v_mfma_f32_16x16x32_bf16 v[12:15], v[112:115], v[104:107], v[12:15]
	v_cvt_pk_bf16_f32 v99, v30, v31
	v_mfma_f32_16x16x32_bf16 v[4:7], v[58:61], v[104:107], v[4:7]
	global_load_dwordx4 v[58:61], v[50:51], off offset:64
	global_load_dwordx4 v[104:107], v[52:53], off offset:64
	global_load_dwordx4 v[112:115], v[46:47], off offset:128
	v_mfma_f32_16x16x32_bf16 v[16:19], v[116:119], v[100:103], v[16:19]
	v_mfma_f32_16x16x32_bf16 v[8:11], v[20:23], v[100:103], v[8:11]
	global_load_dwordx4 v[20:23], v[124:125], off offset:272
	global_load_dwordx4 v[116:119], v[124:125], off offset:256
	global_load_dwordx4 v[28:31], v[48:49], off offset:128
	s_waitcnt vmcnt(1)
	v_cvt_pk_bf16_f32 v116, v116, v117
	v_mfma_f32_16x16x32_bf16 v[12:15], v[120:123], v[100:103], v[12:15]
	v_cvt_pk_bf16_f32 v117, v118, v119
	v_cvt_pk_bf16_f32 v118, v20, v21
	v_cvt_pk_bf16_f32 v119, v22, v23
	v_mfma_f32_16x16x32_bf16 v[4:7], v[54:57], v[100:103], v[4:7]
	v_mfma_f32_16x16x32_bf16 v[16:19], v[108:111], v[96:99], v[16:19]
	global_load_dwordx4 v[54:57], v[50:51], off offset:128
	global_load_dwordx4 v[100:103], v[52:53], off offset:128
	global_load_dwordx4 v[108:111], v[46:47], off offset:192
	v_mfma_f32_16x16x32_bf16 v[8:11], v[58:61], v[96:99], v[8:11]
	global_load_dwordx4 v[58:61], v[124:125], off offset:400
	global_load_dwordx4 v[120:123], v[124:125], off offset:384
	v_mfma_f32_16x16x32_bf16 v[12:15], v[24:27], v[96:99], v[12:15]
	global_load_dwordx4 v[24:27], v[50:51], off offset:192
	v_mfma_f32_16x16x32_bf16 v[4:7], v[104:107], v[96:99], v[4:7]
	global_load_dwordx4 v[104:107], v[48:49], off offset:192
	v_mfma_f32_16x16x32_bf16 v[96:99], v[112:115], v[116:119], v[16:19]
	s_waitcnt vmcnt(2)
	v_cvt_pk_bf16_f32 v16, v120, v121
	v_mfma_f32_16x16x32_bf16 v[112:115], v[28:31], v[116:119], v[12:15]
	v_cvt_pk_bf16_f32 v17, v122, v123
	v_cvt_pk_bf16_f32 v18, v58, v59
	v_cvt_pk_bf16_f32 v19, v60, v61
	v_mfma_f32_16x16x32_bf16 v[28:31], v[54:57], v[116:119], v[8:11]
	ds_read_b64 v[54:55], v92 offset:65024
	s_nop 0
	global_load_dwordx4 v[12:15], v[52:53], off offset:192
	ds_read_b64 v[56:57], v93 offset:65024
	ds_read_b64 v[60:61], v94 offset:65024
	ds_read_b64 v[58:59], v95 offset:65024
	v_mfma_f32_16x16x32_bf16 v[8:11], v[108:111], v[16:19], v[96:99]
	s_waitcnt lgkmcnt(3)
	s_nop 1
	v_lshlrev_b32_e32 v96, 16, v54
	s_waitcnt vmcnt(2)
	v_mfma_f32_16x16x32_bf16 v[24:27], v[24:27], v[16:19], v[28:31]
	s_nop 1
	v_fma_f32 v8, v0, v96, v8
	v_mul_f32_e32 v28, 0x3d372713, v8
	v_mul_f32_e32 v28, v8, v28
	v_fma_f32 v28, v8, v28, v8
	v_mul_f32_e32 v28, 0xc0135761, v28
	v_mfma_f32_16x16x32_bf16 v[20:23], v[100:103], v[116:119], v[4:7]
	v_exp_f32_e32 v28, v28
	s_waitcnt vmcnt(1)
	v_mfma_f32_16x16x32_bf16 v[4:7], v[104:107], v[16:19], v[112:115]
	s_waitcnt vmcnt(0)
	v_mfma_f32_16x16x32_bf16 v[12:15], v[12:15], v[16:19], v[20:23]
	v_add_f32_e32 v18, 1.0, v28
	v_and_b32_e32 v28, 0xffff0000, v54
	v_fma_f32 v9, v1, v28, v9
	v_mul_f32_e32 v28, 0x3d372713, v9
	v_rcp_f32_e32 v20, v18
	v_mul_f32_e32 v28, v9, v28
	v_fma_f32 v28, v9, v28, v9
	v_mul_f32_e32 v28, 0xc0135761, v28
	v_exp_f32_e32 v28, v28
	s_nop 0
	v_add_f32_e32 v22, 1.0, v28
	v_rcp_f32_e32 v29, v22
	v_mul_f32_e32 v19, v8, v20
	v_lshlrev_b32_e32 v20, 16, v55
	v_fma_f32 v10, v2, v20, v10
	v_mul_f32_e32 v20, 0x3d372713, v10
	v_mov_b32_e32 v8, v19
	v_mul_f32_e32 v20, v10, v20
	v_fma_f32 v20, v10, v20, v10
	v_mul_f32_e32 v20, 0xc0135761, v20
	v_exp_f32_e32 v20, v20
	v_and_b32_e32 v19, 0xffff0000, v55
	v_fmac_f32_e32 v11, v3, v19
	v_mul_f32_e32 v19, 0x3d372713, v11
	v_add_f32_e32 v20, 1.0, v20
	v_mul_f32_e32 v19, v11, v19
	v_fma_f32 v19, v11, v19, v11
	v_rcp_f32_e32 v28, v20
	v_mul_f32_e32 v19, 0xc0135761, v19
	v_mul_f32_e32 v9, v9, v29
	v_exp_f32_e32 v19, v19
	v_cvt_pk_bf16_f32 v8, v8, v9
	v_add_f32_e32 v19, 1.0, v19
	v_rcp_f32_e32 v23, v19
	v_mul_f32_e32 v9, v10, v28
	v_add_u32_e32 v21, s12, v82
	v_mul_f32_e32 v10, v11, v23
	s_waitcnt lgkmcnt(2)
; __device__ __forceinline__ unsigned cvt_pk_bf16(float lo, float hi) { unsigned r; asm("v_cvt_pk_bf16_f32 %0, %1, %2" : "=v"(r) : "v"(lo), "v"(hi)); return r; }
; __device__ __forceinline__ float bflo(unsigned w) { return __uint_as_float(w << 16); }
; __device__ __forceinline__ float bfhi(unsigned w) { return __uint_as_float(w & 0xffff0000u); }
; __device__ __forceinline__ float gelu_tanh(float x) { const float u = 0.7978845608028654f * (x + 0.044715f * x * x * x); return x / (1.f + __expf(-2.f * u)); }
; __device__ __forceinline__ void s5out_item(PRef p, int layer, int item, unsigned char* shm) {
;     ...
;         if (nt < 4 || fr < 4) {
; #pragma unroll
;             for (int mi = 0; mi < 4; ++mi) { const int t = tb + mi; const size_t row = nt < 4 ? (size_t)(b * 4096 + (16 * nt + fr) * 64 + t) : (size_t)(RL + b * 256 + fr * 64 + t);
;                 const u32x2 uu = *(const u32x2*)(ul + fr * S5_UP + t * 32 + fq * 8);
;                 const f32x4 y = acc[mi];
;                 u32x2 w; w.x = cvt_pk_bf16(gelu_tanh(y[0] + dv[0] * bflo(uu.x)), gelu_tanh(y[1] + dv[1] * bfhi(uu.x)));
;                 w.y = cvt_pk_bf16(gelu_tanh(y[2] + dv[2] * bflo(uu.y)), gelu_tanh(y[3] + dv[3] * bfhi(uu.y)));
;                 *(u32x2*)(Z + row * 512 + g * 16 + fq * 4) = w; } }
	v_lshlrev_b32_e32 v11, 16, v56
	v_fma_f32 v4, v0, v11, v4
	v_mul_f32_e32 v11, 0x3d372713, v4
	v_mul_f32_e32 v11, v4, v11
	v_fma_f32 v11, v4, v11, v4
	v_mul_f32_e32 v11, 0xc0135761, v11
	v_exp_f32_e32 v18, v11
	v_add_u32_e32 v16, v21, v75
	v_ashrrev_i32_e32 v17, 31, v16
	v_and_b32_e32 v19, 0xffff0000, v56
	v_cvt_pk_bf16_f32 v9, v9, v10
	v_lshlrev_b64 v[10:11], 10, v[16:17]
	v_add_f32_e32 v16, 1.0, v18
	v_fma_f32 v5, v1, v19, v5
	v_mul_f32_e32 v19, 0x3d372713, v5
	v_rcp_f32_e32 v18, v16
	v_mul_f32_e32 v19, v5, v19
	v_fma_f32 v19, v5, v19, v5
	v_mul_f32_e32 v19, 0xc0135761, v19
	v_lshl_add_u64 v[10:11], v[36:37], 0, v[10:11]
	global_store_dwordx2 v[10:11], v[8:9], off
	v_exp_f32_e32 v19, v19
	s_nop 0
	v_add_f32_e32 v17, 1.0, v19
	v_rcp_f32_e32 v20, v17
	v_mul_f32_e32 v4, v4, v18
	v_lshlrev_b32_e32 v16, 16, v57
	v_fma_f32 v6, v2, v16, v6
	v_mul_f32_e32 v16, 0x3d372713, v6
	v_mul_f32_e32 v16, v6, v16
	v_fma_f32 v16, v6, v16, v6
	v_mul_f32_e32 v16, 0xc0135761, v16
	v_exp_f32_e32 v16, v16
	v_and_b32_e32 v11, 0xffff0000, v57
	v_fmac_f32_e32 v7, v3, v11
	v_mul_f32_e32 v11, 0x3d372713, v7
	v_add_f32_e32 v16, 1.0, v16
	v_mul_f32_e32 v11, v7, v11
	v_fma_f32 v11, v7, v11, v7
	v_rcp_f32_e32 v19, v16
	v_mul_f32_e32 v11, 0xc0135761, v11
	v_mul_f32_e32 v5, v5, v20
	v_exp_f32_e32 v11, v11
	v_cvt_pk_bf16_f32 v4, v4, v5
	v_add_f32_e32 v11, 1.0, v11
	v_rcp_f32_e32 v18, v11
	v_mul_f32_e32 v5, v6, v19
	v_add_u32_e32 v8, v21, v83
	v_mul_f32_e32 v6, v7, v18
	s_waitcnt lgkmcnt(1)
	v_lshlrev_b32_e32 v7, 16, v60
	v_fma_f32 v10, v0, v7, v24
	v_mul_f32_e32 v7, 0x3d372713, v10
	v_mul_f32_e32 v7, v10, v7
	v_fma_f32 v7, v10, v7, v10
	v_mul_f32_e32 v7, 0xc0135761, v7
	v_exp_f32_e32 v11, v7
	v_ashrrev_i32_e32 v9, 31, v8
	v_and_b32_e32 v16, 0xffff0000, v60
	v_cvt_pk_bf16_f32 v5, v5, v6
	v_lshlrev_b64 v[6:7], 10, v[8:9]
	v_add_f32_e32 v8, 1.0, v11
	v_fma_f32 v16, v1, v16, v25
	v_mul_f32_e32 v17, 0x3d372713, v16
	v_rcp_f32_e32 v11, v8
	v_mul_f32_e32 v17, v16, v17
	v_fma_f32 v17, v16, v17, v16
	v_mul_f32_e32 v17, 0xc0135761, v17
	v_lshl_add_u64 v[6:7], v[36:37], 0, v[6:7]
	global_store_dwordx2 v[6:7], v[4:5], off
	v_exp_f32_e32 v17, v17
	s_nop 0
	v_add_f32_e32 v9, 1.0, v17
	v_rcp_f32_e32 v18, v9
	v_mul_f32_e32 v6, v10, v11
	v_lshlrev_b32_e32 v10, 16, v61
	v_fma_f32 v10, v2, v10, v26
	v_mul_f32_e32 v11, 0x3d372713, v10
	v_mul_f32_e32 v11, v10, v11
	v_fma_f32 v11, v10, v11, v10
	v_mul_f32_e32 v11, 0xc0135761, v11
	v_exp_f32_e32 v11, v11
	v_mul_f32_e32 v7, v16, v18
	v_and_b32_e32 v9, 0xffff0000, v61
	v_fmac_f32_e32 v27, v3, v9
	v_mul_f32_e32 v9, 0x3d372713, v27
	v_add_f32_e32 v11, 1.0, v11
	v_mul_f32_e32 v9, v27, v9
	v_fma_f32 v9, v27, v9, v27
	v_rcp_f32_e32 v19, v11
	v_mul_f32_e32 v9, 0xc0135761, v9
	v_exp_f32_e32 v9, v9
	v_cvt_pk_bf16_f32 v6, v6, v7
	v_add_f32_e32 v9, 1.0, v9
	v_rcp_f32_e32 v17, v9
	v_mul_f32_e32 v7, v10, v19
	v_add_u32_e32 v4, v21, v84
	v_mul_f32_e32 v8, v27, v17
	s_waitcnt lgkmcnt(0)
	v_lshlrev_b32_e32 v9, 16, v58
	v_fma_f32 v9, v0, v9, v12
	v_mul_f32_e32 v10, 0x3d372713, v9
	v_mul_f32_e32 v10, v9, v10
	v_fma_f32 v10, v9, v10, v9
	v_mul_f32_e32 v10, 0xc0135761, v10
	v_exp_f32_e32 v10, v10
	v_and_b32_e32 v12, 0xffff0000, v58
	v_cvt_pk_bf16_f32 v7, v7, v8
	v_fma_f32 v12, v1, v12, v13
	v_add_f32_e32 v8, 1.0, v10
	v_mul_f32_e32 v13, 0x3d372713, v12
	v_rcp_f32_e32 v11, v8
	v_mul_f32_e32 v13, v12, v13
	v_ashrrev_i32_e32 v5, 31, v4
	v_fma_f32 v13, v12, v13, v12
	v_lshlrev_b64 v[4:5], 10, v[4:5]
	v_mul_f32_e32 v13, 0xc0135761, v13
	v_lshl_add_u64 v[4:5], v[36:37], 0, v[4:5]
	global_store_dwordx2 v[4:5], v[6:7], off
	v_exp_f32_e32 v13, v13
	s_nop 0
	v_add_f32_e32 v10, 1.0, v13
	v_rcp_f32_e32 v16, v10
	v_mul_f32_e32 v6, v9, v11
	v_lshlrev_b32_e32 v9, 16, v59
	v_fma_f32 v9, v2, v9, v14
	v_mul_f32_e32 v11, 0x3d372713, v9
	v_mul_f32_e32 v11, v9, v11
	v_fma_f32 v11, v9, v11, v9
	v_mul_f32_e32 v11, 0xc0135761, v11
	v_exp_f32_e32 v11, v11
	v_mul_f32_e32 v7, v12, v16
	v_and_b32_e32 v10, 0xffff0000, v59
	v_fmac_f32_e32 v15, v3, v10
	v_mul_f32_e32 v10, 0x3d372713, v15
	v_add_f32_e32 v11, 1.0, v11
	v_mul_f32_e32 v10, v15, v10
	v_fma_f32 v10, v15, v10, v15
	v_rcp_f32_e32 v14, v11
	v_mul_f32_e32 v10, 0xc0135761, v10
	v_exp_f32_e32 v10, v10
	v_cvt_pk_bf16_f32 v6, v6, v7
	v_add_f32_e32 v10, 1.0, v10
	v_rcp_f32_e32 v13, v10
	v_mul_f32_e32 v7, v9, v14
	v_add_u32_e32 v4, v21, v85
	v_ashrrev_i32_e32 v5, 31, v4
	v_lshlrev_b64 v[4:5], 10, v[4:5]
	v_lshl_add_u64 v[4:5], v[36:37], 0, v[4:5]
	v_mul_f32_e32 v8, v15, v13
	v_cvt_pk_bf16_f32 v7, v7, v8
	global_store_dwordx2 v[4:5], v[6:7], off
	s_cbranch_scc1 .LBB0_928
	s_barrier
	s_branch .LBB0_918
